# plus dsa_index scoring loop: IKN loads software-pipelined (cb1 + next chunk issued ahead), redundant canonicalize v_max fused
# baseline (speedup 1.0000x reference)
; template <bool DO_SELECT> __device__ __forceinline__ void dsa_index(const Args& a, unsigned char* lds, int tid) {
;     ...
;     for (int r = blockIdx.x; r < M / 8; r += G) {
;         const int b = r >> 9; int qi = r & 511; if ((r >> 9) & 1) qi = 511 - qi;
;         const int q0 = qi * 8, nch = (q0 >> 6) + 1;
;         const size_t rowb = (size_t)b * SEQ;
;         for (int ch = w; ch < nch; ch += 8) {
; #pragma unroll
;             for (int cb = 0; cb < 2; ++cb) {
;                 bf16x8 bfr[4];
; #pragma unroll
;                 for (int ks = 0; ks < 4; ++ks) bfr[ks] = *(const bf16x8*)(IKN + (rowb + ch * 64 + cb * 32 + l32) * 64 + 16 * ks + 8 * hi);
;                 const int key = ch * 64 + cb * 32 + l32;
; #pragma unroll
;                 for (int rb = 0; rb < 2; ++rb) {
;                     f32x16 acc;
; #pragma unroll
;                     for (int e = 0; e < 16; ++e) acc[e] = 0.f;
; #pragma unroll
;                     for (int ks = 0; ks < 4; ++ks) acc = __builtin_amdgcn_mfma_f32_32x32x16_bf16(af[rb][ks], bfr[ks], acc, 0, 0, 0);
; #pragma unroll
;                     for (int jj = 0; jj < 2; ++jj) {
;                         float sc = 0.f;
; #pragma unroll
;                         for (int e = 0; e < 8; ++e) sc = fmaf(fmaxf(acc[8 * jj + e], 0.f), iwv[rb][jj][e >> 2][e & 3], sc);
;                         const int q = rb * 4 + 2 * hi + jj;
;                         if (key > q0 + q) sc = -INFINITY;
;                         scl[q * SEQ + key] = sc;
;                     }
;                 }
;             }
.LBB0_652:
	s_and_b32 s0, s27, 0x1ff
	s_ashr_i32 s2, s27, 9
	s_and_b32 s1, s27, 0x200
	s_xor_b32 s3, s0, 0x1ff
	s_cmp_eq_u32 s1, 0
	s_cselect_b32 s1, s0, s3
	s_ashr_i32 s3, s2, 31
	s_lshl_b64 s[2:3], s[2:3], 12
	s_lshl_b32 s0, s1, 3
	s_lshr_b32 s1, s1, 3
	v_writelane_b32 v253, s2, 53
	s_cmp_gt_i32 s26, s1
	s_nop 0
	v_writelane_b32 v253, s3, 54
	s_cbranch_scc1 .LBB0_655
	v_readlane_b32 s2, v253, 53
	v_readlane_b32 s3, v253, 54
	v_or_b32_e32 v182, s0, v100
	v_or_b32_e32 v183, s0, v104
	v_lshl_add_u64 v[0:1], v[116:117], 0, s[2:3]
	v_lshlrev_b64 v[0:1], 7, v[0:1]
	v_or_b32_e32 v184, s0, v106
	v_or_b32_e32 v185, s0, v108
	v_lshl_add_u64 v[118:119], v[114:115], 0, v[0:1]
	v_mov_b32_e32 v186, v180
	v_mov_b32_e32 v187, v179
	s_mov_b32 s2, s26
	global_load_dwordx4 v[80:83], v[118:119], off
	global_load_dwordx4 v[84:87], v[118:119], off offset:32
	global_load_dwordx4 v[88:91], v[118:119], off offset:64
	global_load_dwordx4 v[92:95], v[118:119], off offset:96
.LBB0_654:
	v_add_co_u32_e32 v232, vcc, 0x1000, v118
	s_nop 1
	v_addc_co_u32_e32 v233, vcc, 0, v119, vcc
	global_load_dwordx4 v[228:231], v[232:233], off
	global_load_dwordx4 v[224:227], v[232:233], off offset:32
	global_load_dwordx4 v[216:219], v[232:233], off offset:64
	global_load_dwordx4 v[220:223], v[232:233], off offset:96
	v_cmp_le_i32_e32 vcc, v187, v182
	s_movk_i32 s3, 0x1000
	v_add_u32_e32 v190, 32, v187
	s_add_i32 s2, s2, 8
	s_mov_b64 s[4:5], 0x10000
	s_cmp_le_i32 s2, s1
	s_waitcnt vmcnt(7)
	v_mfma_f32_32x32x16_bf16 v[0:15], v[16:19], v[80:83], 0
	s_waitcnt vmcnt(6)
	v_mfma_f32_32x32x16_bf16 v[0:15], v[20:23], v[84:87], v[0:15]
	s_waitcnt vmcnt(5)
	v_mfma_f32_32x32x16_bf16 v[0:15], v[24:27], v[88:91], v[0:15]
	s_waitcnt vmcnt(4)
	v_mfma_f32_32x32x16_bf16 v[0:15], v[28:31], v[92:95], v[0:15]
	s_nop 11
	v_max_f32_e32 v0, 0, v0
	v_fma_f32 v0, v0, v60, 0
	v_max_f32_e32 v1, 0, v1
	v_fmac_f32_e32 v0, v1, v61
	v_max_f32_e32 v1, 0, v2
	v_fmac_f32_e32 v0, v1, v62
	v_max_f32_e32 v1, 0, v3
	v_fmac_f32_e32 v0, v1, v63
	v_max_f32_e32 v1, 0, v4
	v_fmac_f32_e32 v0, v1, v56
	v_max_f32_e32 v1, 0, v5
	v_fmac_f32_e32 v0, v1, v57
	v_max_f32_e32 v1, 0, v6
	v_fmac_f32_e32 v0, v1, v58
	v_max_f32_e32 v1, 0, v7
	v_fmac_f32_e32 v0, v1, v59
	v_cndmask_b32_e32 v0, v99, v0, vcc
	v_add_u32_e32 v1, 0xffff0000, v186
	ds_write_b32 v1, v0
	v_max_f32_e32 v0, 0, v8
	v_fma_f32 v0, v0, v52, 0
	v_max_f32_e32 v1, 0, v9
	v_fmac_f32_e32 v0, v1, v53
	v_max_f32_e32 v1, 0, v10
	v_fmac_f32_e32 v0, v1, v54
	v_max_f32_e32 v1, 0, v11
	v_fmac_f32_e32 v0, v1, v55
	v_max_f32_e32 v1, 0, v12
	v_fmac_f32_e32 v0, v1, v48
	v_max_f32_e32 v1, 0, v13
	v_fmac_f32_e32 v0, v1, v49
	v_max_f32_e32 v1, 0, v14
	v_fmac_f32_e32 v0, v1, v50
	v_max_f32_e32 v1, 0, v15
	v_fmac_f32_e32 v0, v1, v51
	v_cmp_le_i32_e32 vcc, v187, v183
	v_add_u32_e32 v1, 0xffff4000, v186
	s_nop 0
	v_cndmask_b32_e32 v0, v99, v0, vcc
	ds_write_b32 v1, v0
	v_mfma_f32_32x32x16_bf16 v[0:15], v[32:35], v[80:83], 0
	v_cmp_le_i32_e32 vcc, v187, v184
	v_mfma_f32_32x32x16_bf16 v[0:15], v[36:39], v[84:87], v[0:15]
	v_mfma_f32_32x32x16_bf16 v[0:15], v[40:43], v[88:91], v[0:15]
	v_mfma_f32_32x32x16_bf16 v[0:15], v[44:47], v[92:95], v[0:15]
	s_nop 11
	v_max_f32_e32 v0, 0, v0
	v_fma_f32 v0, v0, v76, 0
	v_max_f32_e32 v1, 0, v1
	v_fmac_f32_e32 v0, v1, v77
	v_max_f32_e32 v1, 0, v2
	v_fmac_f32_e32 v0, v1, v78
	v_max_f32_e32 v1, 0, v3
	v_fmac_f32_e32 v0, v1, v79
	v_max_f32_e32 v1, 0, v4
	v_fmac_f32_e32 v0, v1, v72
	v_max_f32_e32 v1, 0, v5
	v_fmac_f32_e32 v0, v1, v73
	v_max_f32_e32 v1, 0, v6
	v_fmac_f32_e32 v0, v1, v74
	v_max_f32_e32 v1, 0, v7
	v_fmac_f32_e32 v0, v1, v75
	v_cndmask_b32_e32 v189, v99, v0, vcc
	v_max_f32_e32 v0, 0, v8
	v_fma_f32 v0, v0, v68, 0
	v_max_f32_e32 v1, 0, v9
	v_fmac_f32_e32 v0, v1, v69
	v_max_f32_e32 v1, 0, v10
	v_fmac_f32_e32 v0, v1, v70
	v_max_f32_e32 v1, 0, v11
	v_fmac_f32_e32 v0, v1, v71
	v_max_f32_e32 v1, 0, v12
	v_fmac_f32_e32 v0, v1, v64
	v_max_f32_e32 v1, 0, v13
	v_fmac_f32_e32 v0, v1, v65
	v_max_f32_e32 v1, 0, v14
	v_fmac_f32_e32 v0, v1, v66
	v_max_f32_e32 v1, 0, v15
	v_fmac_f32_e32 v0, v1, v67
	v_cmp_le_i32_e32 vcc, v187, v185
	v_add_u32_e32 v187, 0x200, v187
	s_nop 0
	v_cndmask_b32_e32 v188, v99, v0, vcc
	v_lshl_add_u64 v[118:119], v[118:119], 0, s[4:5]
	global_load_dwordx4 v[80:83], v[118:119], off
	global_load_dwordx4 v[84:87], v[118:119], off offset:32
	global_load_dwordx4 v[88:91], v[118:119], off offset:64
	global_load_dwordx4 v[92:95], v[118:119], off offset:96
	v_cmp_le_i32_e32 vcc, v190, v182
	s_waitcnt vmcnt(7)
	v_mfma_f32_32x32x16_bf16 v[0:15], v[16:19], v[228:231], 0
	s_waitcnt vmcnt(6)
	v_mfma_f32_32x32x16_bf16 v[0:15], v[20:23], v[224:227], v[0:15]
	s_waitcnt vmcnt(5)
; template <bool DO_SELECT> __device__ __forceinline__ void dsa_index(const Args& a, unsigned char* lds, int tid) {
;     ...
;         for (int ch = w; ch < nch; ch += 8) {
; #pragma unroll
;             for (int cb = 0; cb < 2; ++cb) {
;                 bf16x8 bfr[4];
; #pragma unroll
;                 for (int ks = 0; ks < 4; ++ks) bfr[ks] = *(const bf16x8*)(IKN + (rowb + ch * 64 + cb * 32 + l32) * 64 + 16 * ks + 8 * hi);
;                 const int key = ch * 64 + cb * 32 + l32;
; #pragma unroll
;                 for (int rb = 0; rb < 2; ++rb) {
;                     f32x16 acc;
; #pragma unroll
;                     for (int e = 0; e < 16; ++e) acc[e] = 0.f;
; #pragma unroll
;                     for (int ks = 0; ks < 4; ++ks) acc = __builtin_amdgcn_mfma_f32_32x32x16_bf16(af[rb][ks], bfr[ks], acc, 0, 0, 0);
; #pragma unroll
;                     for (int jj = 0; jj < 2; ++jj) {
;                         float sc = 0.f;
; #pragma unroll
;                         for (int e = 0; e < 8; ++e) sc = fmaf(fmaxf(acc[8 * jj + e], 0.f), iwv[rb][jj][e >> 2][e & 3], sc);
;                         const int q = rb * 4 + 2 * hi + jj;
;                         if (key > q0 + q) sc = -INFINITY;
;                         scl[q * SEQ + key] = sc;
;                     }
;                 }
;             }
;         }
;         __syncthreads();
;         if (r + G < M / 8) IDX_LOAD_UNIT(r + G);
	v_mfma_f32_32x32x16_bf16 v[0:15], v[24:27], v[216:219], v[0:15]
	s_waitcnt vmcnt(4)
	v_mfma_f32_32x32x16_bf16 v[0:15], v[28:31], v[220:223], v[0:15]
	s_nop 11
	v_max_f32_e32 v0, 0, v0
	v_fma_f32 v0, v0, v60, 0
	v_max_f32_e32 v1, 0, v1
	v_fmac_f32_e32 v0, v1, v61
	v_max_f32_e32 v1, 0, v2
	v_fmac_f32_e32 v0, v1, v62
	v_max_f32_e32 v1, 0, v3
	v_fmac_f32_e32 v0, v1, v63
	v_max_f32_e32 v1, 0, v4
	v_fmac_f32_e32 v0, v1, v56
	v_max_f32_e32 v1, 0, v5
	v_fmac_f32_e32 v0, v1, v57
	v_max_f32_e32 v1, 0, v6
	v_fmac_f32_e32 v0, v1, v58
	v_max_f32_e32 v1, 0, v7
	v_fmac_f32_e32 v0, v1, v59
	v_cndmask_b32_e32 v0, v99, v0, vcc
	v_add_u32_e32 v1, 0xffff0080, v186
	ds_write_b32 v1, v0
	v_max_f32_e32 v0, 0, v8
	v_fma_f32 v0, v0, v52, 0
	v_max_f32_e32 v1, 0, v9
	v_fmac_f32_e32 v0, v1, v53
	v_max_f32_e32 v1, 0, v10
	v_fmac_f32_e32 v0, v1, v54
	v_max_f32_e32 v1, 0, v11
	v_fmac_f32_e32 v0, v1, v55
	v_max_f32_e32 v1, 0, v12
	v_fmac_f32_e32 v0, v1, v48
	v_max_f32_e32 v1, 0, v13
	v_fmac_f32_e32 v0, v1, v49
	v_max_f32_e32 v1, 0, v14
	v_fmac_f32_e32 v0, v1, v50
	v_max_f32_e32 v1, 0, v15
	v_fmac_f32_e32 v0, v1, v51
	v_cmp_le_i32_e32 vcc, v190, v183
	v_add_u32_e32 v1, 0xffff4080, v186
	s_nop 0
	v_cndmask_b32_e32 v0, v99, v0, vcc
	ds_write_b32 v1, v0
	v_mfma_f32_32x32x16_bf16 v[0:15], v[32:35], v[228:231], 0
	v_cmp_le_i32_e32 vcc, v190, v184
	v_mfma_f32_32x32x16_bf16 v[0:15], v[36:39], v[224:227], v[0:15]
	v_mfma_f32_32x32x16_bf16 v[0:15], v[40:43], v[216:219], v[0:15]
	v_mfma_f32_32x32x16_bf16 v[0:15], v[44:47], v[220:223], v[0:15]
	s_nop 11
	v_max_f32_e32 v0, 0, v0
	v_fma_f32 v0, v0, v76, 0
	v_max_f32_e32 v1, 0, v1
	v_fmac_f32_e32 v0, v1, v77
	v_max_f32_e32 v1, 0, v2
	v_fmac_f32_e32 v0, v1, v78
	v_max_f32_e32 v1, 0, v3
	v_fmac_f32_e32 v0, v1, v79
	v_max_f32_e32 v1, 0, v4
	v_fmac_f32_e32 v0, v1, v72
	v_max_f32_e32 v1, 0, v5
	v_fmac_f32_e32 v0, v1, v73
	v_max_f32_e32 v1, 0, v6
	v_fmac_f32_e32 v0, v1, v74
	v_max_f32_e32 v1, 0, v7
	v_fmac_f32_e32 v0, v1, v75
	v_cndmask_b32_e32 v0, v99, v0, vcc
	ds_write2_b32 v186, v189, v0 offset1:32
	v_max_f32_e32 v0, 0, v8
	v_fma_f32 v0, v0, v68, 0
	v_max_f32_e32 v1, 0, v9
	v_fmac_f32_e32 v0, v1, v69
	v_max_f32_e32 v1, 0, v10
	v_fmac_f32_e32 v0, v1, v70
	v_max_f32_e32 v1, 0, v11
	v_fmac_f32_e32 v0, v1, v71
	v_max_f32_e32 v1, 0, v12
	v_fmac_f32_e32 v0, v1, v64
	v_max_f32_e32 v1, 0, v13
	v_fmac_f32_e32 v0, v1, v65
	v_max_f32_e32 v1, 0, v14
	v_fmac_f32_e32 v0, v1, v66
	v_max_f32_e32 v1, 0, v15
	v_fmac_f32_e32 v0, v1, v67
	v_cmp_le_i32_e32 vcc, v190, v185
	v_add_u32_e32 v1, 0x4000, v186
	v_add_u32_e32 v186, 0x800, v186
	v_cndmask_b32_e32 v0, v99, v0, vcc
	ds_write2_b32 v1, v188, v0 offset1:32
	s_cbranch_scc1 .LBB0_654
.LBB0_655:
	s_waitcnt vmcnt(0)
	v_readlane_b32 s1, v248, 59
	s_add_i32 s27, s27, s1
	s_cmpk_gt_i32 s27, 0xfff
	s_cselect_b64 s[2:3], -1, 0
	v_writelane_b32 v253, s2, 55
	s_and_b64 vcc, exec, s[2:3]
	s_waitcnt lgkmcnt(0)
	v_writelane_b32 v253, s3, 56
	s_barrier
	s_cbranch_vccnz .LBB0_657
	s_ashr_i32 s2, s27, 9
	s_lshl_b32 s4, s27, 3
	s_ashr_i32 s3, s2, 31
	s_and_b32 s4, s4, 0xff8
	s_and_b32 s1, s27, 0x200
	s_lshl_b64 s[2:3], s[2:3], 12
	s_xor_b32 s5, s4, 0xff8
	s_cmp_eq_u32 s1, 0
	s_cselect_b32 s1, s4, s5
	s_or_b32 s1, s2, s1
	v_or_b32_e32 v0, s1, v96
	s_movk_i32 s2, 0x1200
	v_mad_u64_u32 v[0:1], s[4:5], v0, s2, v[112:113]
	v_mad_i32_i24 v1, s3, v181, v1
	global_load_dwordx4 v[16:19], v[0:1], off offset:3072
	global_load_dwordx4 v[20:23], v[0:1], off offset:3104
	global_load_dwordx4 v[24:27], v[0:1], off offset:3136
	global_load_dwordx4 v[28:31], v[0:1], off offset:3168
	v_or_b32_e32 v0, s1, v110
	v_mad_u64_u32 v[0:1], s[4:5], v0, s2, v[112:113]
	v_mad_i32_i24 v1, s3, v181, v1
	global_load_dwordx4 v[32:35], v[0:1], off offset:3072
	global_load_dwordx4 v[36:39], v[0:1], off offset:3104
	global_load_dwordx4 v[40:43], v[0:1], off offset:3136
	global_load_dwordx4 v[44:47], v[0:1], off offset:3168
	v_mov_b32_e32 v1, s3
	v_or_b32_e32 v0, s1, v100
	v_readlane_b32 s4, v249, 37
	v_lshlrev_b64 v[0:1], 5, v[0:1]
	v_readlane_b32 s5, v249, 38
	s_nop 1
	v_lshl_add_u64 v[0:1], s[4:5], 0, v[0:1]
	global_load_dwordx4 v[48:51], v[0:1], off offset:48
	global_load_dwordx4 v[52:55], v[0:1], off offset:32
	global_load_dwordx4 v[56:59], v[0:1], off offset:16
	global_load_dwordx4 v[60:63], v[0:1], off
	v_mov_b32_e32 v1, s3
	v_or_b32_e32 v0, s1, v106
	v_lshlrev_b64 v[0:1], 5, v[0:1]
	v_lshl_add_u64 v[0:1], s[4:5], 0, v[0:1]
	global_load_dwordx4 v[64:67], v[0:1], off offset:48
	global_load_dwordx4 v[68:71], v[0:1], off offset:32
	global_load_dwordx4 v[72:75], v[0:1], off offset:16
	global_load_dwordx4 v[76:79], v[0:1], off
